# attention: next work item's Q/K/V prologue loads issued inside the last softmax step of the current item (prologue de-serialisation)
# speedup vs baseline: 1.0093x; 1.0093x over previous
; template <bool MLA>
; DI void attn_phase(const int TID, const int BID, LAS unsigned char* lds, const Params& p, bool need_ctx) {
;     ...
;     const int tid = TID, wid = tid >> 6, lane = tid & 63, r = lane & 31, hh = lane >> 5;
;     const int n_items = 1024 + (need_ctx ? 128 : 0);
;     bf16_t* O = P_WSB(OFF_H);
;     for (int item = BID; item < n_items; item += gridDim.x) {
;         int b, head, row0, nk;
;         if (item < 1024) {
;             const int rnd = item >> 8, w = item & 255, xcd = w & 7, slot = w >> 3, qb = slot & 7;
;             if (MLA) { const int grp = (rnd * 8 + xcd) * 4 + (slot >> 3); b = grp >> 4; head = grp & 15; }
;             else { const int grp = rnd * 8 + xcd; b = grp >> 2; head = (grp & 3) * 4 + (slot >> 3); }
;             row0 = b * 2048 + qb * 256; nk = NKEY;
;         }
;         else { const int it = item - 1024; b = it >> 4; head = it & 15; row0 = TL + b * 256; nk = 256; }
;         const int kvh = MLA ? head : (head >> 2);
;         const bf16_t* Kb = P_WSB(OFF_K) + (size_t)(b * NKV + kvh) * NKEY * 64;
;         const bf16_t* Vb = P_WSB(OFF_VT) + (size_t)(b * NKV + kvh) * NKEY * 64;
;         const bf16_t* Pb = P_WSB(OFF_KPE) + (size_t)b * NKEY * 32;
.LBB0_293:
	s_andn2_b64 vcc, exec, s[0:1]
	s_cbranch_vccnz .LBB0_773
	s_add_i32 s0, s23, 0x22040
	v_writelane_b32 v255, s0, 32
	s_nop 0
	v_readlane_b32 s0, v255, 21
	s_cmp_lt_i32 s0, 2
	s_mov_b64 s[0:1], -1
	s_cbranch_scc1 .LBB0_501
	v_readlane_b32 s0, v255, 21
	s_cmp_gt_i32 s0, 2
	v_readlane_b32 s0, v255, 24
	v_readlane_b32 s1, v255, 25
	s_mov_b64 s[2:3], -1
	s_nop 0
	v_cndmask_b32_e64 v0, 0, 1, s[0:1]
	v_cmp_ne_u32_e64 s[0:1], 1, v0
	s_cbranch_scc0 .LBB0_340
	v_readlane_b32 s2, v255, 27
	s_cmp_lt_i32 s2, 3
	s_movk_i32 s2, 0x480
	s_cselect_b32 s8, s2, 0x400
	v_readlane_b32 s3, v255, 28
	s_cmp_lt_i32 s83, s8
	s_cselect_b64 s[2:3], -1, 0
	v_cndmask_b32_e64 v0, 0, 1, s[2:3]
	s_mov_b64 s[4:5], -1
	s_and_b64 vcc, exec, s[0:1]
	v_cmp_ne_u32_e64 s[2:3], 1, v0
	s_cbranch_vccnz .LBB0_318
	s_and_b64 vcc, exec, s[2:3]
	s_cbranch_vccnz .LBB0_317
	v_and_b32_e32 v208, 31, v174
	v_bfe_u32 v209, v174, 5, 1
	v_lshrrev_b32_e32 v210, 6, v174
	v_lshrrev_b32_e32 v211, 3, v174
	v_and_b32_e32 v212, 7, v174
	v_mov_b32_e32 v213, s23
	s_movk_i32 s15, 0xd0
	v_mad_u32_u24 v243, v208, s15, v213
	v_lshl_add_u32 v243, v209, 4, v243
	v_mad_u32_u24 v218, v211, s15, v213
	v_lshl_add_u32 v219, v212, 3, v218
	v_add_u32_e32 v219, 0x80, v219
	v_lshl_add_u32 v218, v212, 4, v218
	s_movk_i32 s15, 0xc0
	v_bfe_u32 v214, v174, 2, 2
	v_lshl_add_u32 v214, v209, 2, v214
	v_mad_u32_u24 v220, v214, s15, v213
	v_bfe_u32 v215, v174, 4, 1
	v_and_b32_e32 v216, 3, v174
	v_lshlrev_b32_e32 v215, 5, v215
	v_lshl_add_u32 v215, v216, 3, v215
	v_add_u32_e32 v220, v220, v215
	v_add_u32_e32 v220, 0x6800, v220
	v_mad_u32_u24 v221, v211, s15, v213
	v_lshl_add_u32 v221, v212, 4, v221
	v_add_u32_e32 v221, 0x6800, v221
	v_lshlrev_b32_e32 v225, 7, v211
	v_lshl_add_u32 v225, v212, 4, v225
	v_lshlrev_b32_e32 v165, 6, v211
	v_lshl_add_u32 v165, v212, 3, v165
	v_lshl_add_u32 v217, v210, 5, v208
	s_movk_i32 s15, 0xc00
	v_mul_u32_u24_e32 v171, s15, v217
	v_lshl_add_u32 v171, v209, 4, v171
	v_lshlrev_b32_e32 v172, 11, v217
	v_lshl_add_u32 v172, v209, 4, v172
	v_mov_b32_e32 v167, 0
	v_mov_b32_e32 v246, 0x3f803f80
	v_mov_b32_e32 v247, 0x3f803f80
	v_mov_b32_e32 v248, 0x3f803f80
	v_mov_b32_e32 v249, 0x3f803f80
	v_readfirstlane_b32 s58, v210
	s_mov_b32 s6, s83
	s_lshr_b32 s58, s58, 2
	s_cmpk_gt_i32 s6, 0x3ff
	s_cbranch_scc0 .Lamla_mainitem_first
	s_add_i32 s21, s6, 0xfffffc00
	s_lshr_b32 s15, s21, 4
	s_and_b32 s18, s21, 15
	s_lshl_b32 s20, s15, 8
	s_add_i32 s20, s20, 0x4000
	s_mov_b32 s7, 0
	s_branch .Lamla_decoded_first

; #define AT_GLOADK(k0) do { kreg = *(const u32x4*)(Kb + (size_t)((k0) + (tid >> 3)) * 64 + (tid & 7) * 8); \
;             if (MLA) preg = *(const u32x2*)(Pb + (size_t)((k0) + (tid >> 3)) * 32 + (tid & 7) * 4); } while (0)
; #define AT_GLOADV(k0) do { vreg = *(const u32x4*)(Vb + (size_t)((k0) + (tid >> 3)) * 64 + (tid & 7) * 8); } while (0)
; #define AT_WRITEK(buf) do { *(LAS u32x4*)(lds + (buf) * KBUF + (tid >> 3) * KSTR + (tid & 7) * 16) = kreg; \
;             if (MLA) *(LAS u32x2*)(lds + (buf) * KBUF + (tid >> 3) * KSTR + 128 + (tid & 7) * 8) = preg; } while (0)
; #define AT_WRITEV(buf) do { *(LAS u32x4*)(lds + 2 * KBUF + (buf) * VBUF + (tid >> 3) * VSTR + (tid & 7) * 16) = vreg; } while (0)
; template <bool MLA>
; DI void attn_phase(const int TID, const int BID, LAS unsigned char* lds, const Params& p, bool need_ctx) {
;     ...
;         f32x16 o0, o1, sa0, sa1, sb0, sb1;
; #pragma unroll
;         for (int j = 0; j < 16; ++j) { o0[j] = 0.f; o1[j] = 0.f; }
;         float mrun = -1e30f, lsum = 0.f;
;         if (wid >= 4) __builtin_amdgcn_s_setprio(1);
;         const int ntile = nk >> 6;
;         AT_GLOADK(0); AT_GLOADV(0); AT_WRITEK(0); AT_WRITEV(0);
;         AT_GLOADK(64); AT_WRITEK(1);
;         __syncthreads();
;         AT_QK(sa0, sa1, 0);
;         __syncthreads();
.Lamla_item:
	s_mov_b32 s52, 0x3000
	s_mov_b32 s53, 0x6000
	s_mov_b32 s54, 0
	v_mov_b64_e32 v[0:1], 0
	v_mov_b64_e32 v[2:3], 0
	v_mov_b64_e32 v[4:5], 0
	v_mov_b64_e32 v[6:7], 0
	v_mov_b64_e32 v[8:9], 0
	v_mov_b64_e32 v[10:11], 0
	v_mov_b64_e32 v[12:13], 0
	v_mov_b64_e32 v[14:15], 0
	v_mov_b64_e32 v[16:17], 0
	v_mov_b64_e32 v[18:19], 0
	v_mov_b64_e32 v[20:21], 0
	v_mov_b64_e32 v[22:23], 0
	v_mov_b64_e32 v[24:25], 0
	v_mov_b64_e32 v[26:27], 0
	v_mov_b64_e32 v[28:29], 0
	v_mov_b64_e32 v[30:31], 0
	v_mov_b32_e32 v162, 0xf149f2ca
	v_mov_b32_e32 v164, 0xf149f2ca
	v_mov_b32_e32 v163, 0x7149f2ca
	v_mov_b64_e32 v[226:227], 0
	v_mov_b64_e32 v[228:229], 0
	v_mov_b64_e32 v[230:231], 0
	v_mov_b64_e32 v[232:233], 0
	v_mov_b64_e32 v[234:235], 0
	v_mov_b64_e32 v[236:237], 0
	v_mov_b64_e32 v[238:239], 0
	v_mov_b64_e32 v[240:241], 0
	s_barrier
	s_waitcnt vmcnt(7)
	ds_write_b128 v218, v[136:139]
	s_waitcnt vmcnt(6)
	ds_write_b64 v219, v[208:209]
	s_waitcnt vmcnt(5)
	ds_write_b128 v218, v[140:143] offset:13312
	s_waitcnt vmcnt(4)
	ds_write_b64 v219, v[210:211] offset:13312
	s_waitcnt vmcnt(3)
	ds_write_b128 v221, v[144:147]
	s_waitcnt lgkmcnt(0)
	s_barrier
	s_cmp_eq_u32 s58, 0
	s_cbranch_scc1 .Lamla_prio
	s_setprio 1

; template <bool MLA>
; DI void attn_phase(const int TID, const int BID, LAS unsigned char* lds, const Params& p, bool need_ctx) {
;     ...
;     for (int item = BID; item < n_items; item += gridDim.x) {
;         int b, head, row0, nk;
;         if (item < 1024) {
;             const int rnd = item >> 8, w = item & 255, xcd = w & 7, slot = w >> 3, qb = slot & 7;
;             if (MLA) { const int grp = (rnd * 8 + xcd) * 4 + (slot >> 3); b = grp >> 4; head = grp & 15; }
;             else { const int grp = rnd * 8 + xcd; b = grp >> 2; head = (grp & 3) * 4 + (slot >> 3); }
;             row0 = b * 2048 + qb * 256; nk = NKEY;
;         }
;         else { const int it = item - 1024; b = it >> 4; head = it & 15; row0 = TL + b * 256; nk = 256; }
;         const int kvh = MLA ? head : (head >> 2);
;         const bf16_t* Kb = P_WSB(OFF_K) + (size_t)(b * NKV + kvh) * NKEY * 64;
;         const bf16_t* Vb = P_WSB(OFF_VT) + (size_t)(b * NKV + kvh) * NKEY * 64;
;         const bf16_t* Pb = P_WSB(OFF_KPE) + (size_t)b * NKEY * 32;
;         bf16x8 qf[NKS];
;         {
;             const bf16_t* qp = P_WSB(OFF_Q) + (size_t)(row0 + wid * 32 + r) * QS + head * DK + hh * 8;
; #pragma unroll
;             for (int ks = 0; ks < NKS; ++ks) qf[ks] = *(const bf16x8*)(qp + ks * 16);
;         }
;         u32x4 kreg, vreg; u32x2 preg = {0u, 0u};
.Lamla_noresc_9:
	s_waitcnt lgkmcnt(0)
	s_barrier
	s_add_i32 s59, s6, s31
	s_cmp_ge_i32 s59, s8
	s_cbranch_scc1 .Lamla_nonext
	s_cmpk_gt_i32 s59, 0x3ff
	s_cbranch_scc0 .Lamla_mainitem_next
	s_add_i32 s21, s59, 0xfffffc00
	s_lshr_b32 s15, s21, 4
	s_and_b32 s18, s21, 15
	s_lshl_b32 s20, s15, 8
	s_add_i32 s20, s20, 0x4000
	s_mov_b32 s7, 0
	s_branch .Lamla_decoded_next
.Lamla_mainitem_next:
	s_lshr_b32 s21, s59, 8
	s_and_b32 s55, s59, 7
	s_lshl_b32 s21, s21, 3
	s_add_i32 s21, s21, s55
	s_bfe_u32 s55, s59, 0x30003
	s_bfe_u32 s56, s59, 0x20006
	s_lshl_b32 s21, s21, 2
	s_add_i32 s21, s21, s56
	s_lshr_b32 s15, s21, 4
	s_and_b32 s18, s21, 15
	s_lshl_b32 s20, s15, 11
	s_lshl_b32 s55, s55, 8
	s_add_i32 s20, s20, s55
	s_mov_b32 s7, 16
.Lamla_decoded_next:
	s_mov_b32 s19, s18
	s_lshl_b32 s21, s15, 4
	s_add_i32 s21, s21, s19
	s_mul_i32 s21, s21, 0x48000
	s_add_u32 s2, s26, s21
	s_addc_u32 s3, s27, 0
	v_readlane_b32 s60, v254, 36
	v_readlane_b32 s61, v254, 37
	s_add_u32 s4, s60, s21
	s_addc_u32 s5, s61, 0
	v_readlane_b32 s60, v254, 38
	v_readlane_b32 s61, v254, 39
	s_mul_i32 s21, s15, 0x24000
	s_add_u32 s10, s60, s21
	s_addc_u32 s11, s61, 0
	v_readlane_b32 s60, v254, 27
	v_readlane_b32 s61, v254, 28
	s_mul_i32 s21, s20, 0xc00
	s_mul_i32 s55, s18, 0xc0
	s_add_i32 s21, s21, s55
	s_add_u32 s12, s60, s21
	s_addc_u32 s13, s61, 0
	v_readlane_b32 s60, v254, 34
	v_readlane_b32 s61, v254, 35
	s_lshl_b32 s21, s20, 11
	s_lshl_b32 s55, s18, 7
	s_add_i32 s21, s21, s55
	s_add_u32 s62, s60, s21
	s_addc_u32 s63, s61, 0
	global_load_dwordx4 v[112:115], v171, s[12:13]
	global_load_dwordx4 v[116:119], v171, s[12:13] offset:32
	global_load_dwordx4 v[120:123], v171, s[12:13] offset:64
	global_load_dwordx4 v[124:127], v171, s[12:13] offset:96
	global_load_dwordx4 v[128:131], v171, s[12:13] offset:128
	global_load_dwordx4 v[132:135], v171, s[12:13] offset:160
	global_load_dwordx4 v[136:139], v225, s[2:3]
	global_load_dwordx2 v[208:209], v165, s[10:11]
	s_add_u32 s2, s2, 0x2000
	s_addc_u32 s3, s3, 0
	s_add_u32 s10, s10, 0x1000
	s_addc_u32 s11, s11, 0
	global_load_dwordx4 v[140:143], v225, s[2:3]
	global_load_dwordx2 v[210:211], v165, s[10:11]
	s_add_u32 s2, s2, 0x2000
	s_addc_u32 s3, s3, 0
	s_add_u32 s10, s10, 0x1000
	s_addc_u32 s11, s11, 0
	global_load_dwordx4 v[144:147], v225, s[4:5]
	s_add_u32 s4, s4, 0x2000
	s_addc_u32 s5, s5, 0
	global_load_dwordx4 v[152:155], v225, s[2:3]
	global_load_dwordx2 v[160:161], v165, s[10:11]
	s_add_u32 s2, s2, 0x2000
	s_addc_u32 s3, s3, 0
	s_add_u32 s10, s10, 0x1000
	s_addc_u32 s11, s11, 0
	global_load_dwordx4 v[156:159], v225, s[4:5]
	s_add_u32 s4, s4, 0x2000
	s_addc_u32 s5, s5, 0
.Lamla_nonext:
	ds_read_b64_tr_b16 v[192:193], v223 offset:3072
	ds_read_b64_tr_b16 v[194:195], v223 offset:4608
	ds_read_b64_tr_b16 v[196:197], v223 offset:3136
	ds_read_b64_tr_b16 v[198:199], v223 offset:4672
	v_mfma_f32_32x32x16_bf16 v[0:15], v[176:179], v[96:99], v[0:15]
	v_max3_f32 v168, v64, v65, v66
	v_max3_f32 v170, v80, v81, v82
	v_max3_f32 v168, v168, v67, v68
	v_max3_f32 v170, v170, v83, v84
	v_max3_f32 v168, v168, v69, v70
	v_max3_f32 v170, v170, v85, v86
	v_max3_f32 v168, v168, v71, v72
	v_max3_f32 v170, v170, v87, v88
	v_max3_f32 v168, v168, v73, v74
	v_max3_f32 v170, v170, v89, v90
	v_max3_f32 v168, v168, v75, v76
	v_max3_f32 v170, v170, v91, v92
	s_mov_b32 s55, s52
	s_mov_b32 s52, s53
	s_mov_b32 s53, s54
	s_mov_b32 s54, s55
	s_mov_b32 s9, 0
	ds_read_b64_tr_b16 v[200:201], v223 offset:9216
	ds_read_b64_tr_b16 v[202:203], v223 offset:10752
	ds_read_b64_tr_b16 v[204:205], v223 offset:9280
	ds_read_b64_tr_b16 v[206:207], v223 offset:10816
	v_mfma_f32_32x32x16_bf16 v[16:31], v[180:183], v[96:99], v[16:31]
	v_max3_f32 v168, v168, v77, v78
	v_max3_f32 v170, v170, v93, v94
	v_max_f32_e32 v168, v168, v79
	v_max_f32_e32 v170, v170, v95
	v_max_f32_e32 v168, v168, v170
	v_mov_b32_e32 v170, v168
	s_nop 1
	v_permlane32_swap_b32_e32 v168, v170
	v_max_f32_e32 v168, v168, v170
	v_mul_f32_e32 v168, 0x3e16c740, v168
	v_cmp_gt_f32_e32 vcc, v168, v164
	s_cbranch_vccz .Lamla_nors_10
	v_max_f32_e32 v170, v162, v168
	v_sub_f32_e32 v166, v162, v170
	v_exp_f32_e32 v166, v166
	v_mov_b32_e32 v162, v170
	v_add_f32_e32 v164, 0x41000000, v170
	v_xor_b32_e32 v163, 0x80000000, v170
	s_mov_b32 s9, 1

; #define AT_STEP(SC0, SC1, SN0, SN1, t, DOK, DOV) do { \
;             if (DOK) AT_GLOADK(((t) + 2) * 64); \
;             if (DOV) { AT_GLOADV(((t) + 1) * 64); AT_QK(SN0, SN1, ((t) + 1) & 1); } \
;             AT_SMPV(SC0, SC1, (t) & 1); \
;             if (DOK) AT_WRITEK((t) & 1); \
;             if (DOV) AT_WRITEV(((t) + 1) & 1); \
;             __syncthreads(); } while (0)
; #define AT_PK4(OX, jg) u32x2 { pk_bf16(OX[4 * (jg)] * inv, OX[4 * (jg) + 1] * inv), pk_bf16(OX[4 * (jg) + 2] * inv, OX[4 * (jg) + 3] * inv) }
; template <bool MLA>
; DI void attn_phase(const int TID, const int BID, LAS unsigned char* lds, const Params& p, bool need_ctx) {
;     ...
;         AT_STEP(sa0, sa1, sb0, sb1, t, false, true);
;         AT_STEP(sb0, sb1, sa0, sa1, t + 1, false, false);
;         __builtin_amdgcn_s_setprio(0);
;         lsum = xsum32(lsum);
;         const float inv = 1.f / lsum;
;         bf16_t* op = O + (size_t)(row0 + wid * 32 + r) * 1024 + head * 64 + 8 * hh;
;     ...
; #pragma unroll
;         for (int k = 0; k < 2; ++k) {
;             const u32x2 a = AT_PK4(o0, 2 * k), b2 = AT_PK4(o0, 2 * k + 1), c = AT_PK4(o1, 2 * k), d = AT_PK4(o1, 2 * k + 1);
;             const u32x2 s0 = __builtin_amdgcn_permlane32_swap(a[0], b2[0], false, false), s1 = __builtin_amdgcn_permlane32_swap(a[1], b2[1], false, false);
;             const u32x2 t0 = __builtin_amdgcn_permlane32_swap(c[0], d[0], false, false), t1 = __builtin_amdgcn_permlane32_swap(c[1], d[1], false, false);
;             const u32x4 w0 = {s0[0], s1[0], s0[1], s1[1]}, w1 = {t0[0], t1[0], t0[1], t1[1]};
;             *(u32x4*)(op + 16 * k) = w0; *(u32x4*)(op + 32 + 16 * k) = w1;
;         }
.Lamla_noresc_11:
	s_waitcnt lgkmcnt(0)
	s_barrier
	ds_read_b64_tr_b16 v[192:193], v222 offset:3072
	ds_read_b64_tr_b16 v[194:195], v222 offset:4608
	ds_read_b64_tr_b16 v[196:197], v222 offset:3136
	ds_read_b64_tr_b16 v[198:199], v222 offset:4672
	v_mfma_f32_32x32x16_bf16 v[0:15], v[176:179], v[96:99], v[0:15]
	s_mov_b32 s55, s52
	s_mov_b32 s52, s53
	s_mov_b32 s53, s54
	s_mov_b32 s54, s55
	ds_read_b64_tr_b16 v[200:201], v222 offset:9216
	ds_read_b64_tr_b16 v[202:203], v222 offset:10752
	ds_read_b64_tr_b16 v[204:205], v222 offset:9280
	ds_read_b64_tr_b16 v[206:207], v222 offset:10816
	v_mfma_f32_32x32x16_bf16 v[16:31], v[180:183], v[96:99], v[16:31]
	v_mfma_f32_32x32x16_bf16 v[226:241], v[246:249], v[96:99], v[226:241]
	v_mfma_f32_32x32x16_bf16 v[0:15], v[184:187], v[104:107], v[0:15]
	v_mfma_f32_32x32x16_bf16 v[16:31], v[188:191], v[104:107], v[16:31]
	v_mfma_f32_32x32x16_bf16 v[226:241], v[246:249], v[104:107], v[226:241]
	s_waitcnt lgkmcnt(6)
	v_mfma_f32_32x32x16_bf16 v[0:15], v[192:195], v[100:103], v[0:15]
	s_waitcnt lgkmcnt(4)
	v_mfma_f32_32x32x16_bf16 v[16:31], v[196:199], v[100:103], v[16:31]
	v_mfma_f32_32x32x16_bf16 v[226:241], v[246:249], v[100:103], v[226:241]
	s_waitcnt lgkmcnt(2)
	v_mfma_f32_32x32x16_bf16 v[0:15], v[200:203], v[108:111], v[0:15]
	s_waitcnt lgkmcnt(0)
	v_mfma_f32_32x32x16_bf16 v[16:31], v[204:207], v[108:111], v[16:31]
	v_mfma_f32_32x32x16_bf16 v[226:241], v[246:249], v[108:111], v[226:241]
	s_setprio 0
	s_nop 11
	v_div_scale_f32 v148, s[60:61], v226, v226, 1.0
	v_rcp_f32_e32 v149, v148
	s_nop 0
	v_fma_f32 v150, -v148, v149, 1.0
	v_fmac_f32_e32 v149, v150, v149
	v_div_scale_f32 v150, vcc, 1.0, v226, 1.0
	v_mul_f32_e32 v151, v150, v149
	v_fma_f32 v173, -v148, v151, v150
	v_fmac_f32_e32 v151, v173, v149
	v_fma_f32 v148, -v148, v151, v150
	s_nop 1
	v_div_fmas_f32 v148, v148, v149, v151
	v_div_fixup_f32 v166, v148, v226, 1.0
	v_pk_mul_f32 v[0:1], v[0:1], v[166:167] op_sel_hi:[1,0]
	v_pk_mul_f32 v[2:3], v[2:3], v[166:167] op_sel_hi:[1,0]
	v_pk_mul_f32 v[4:5], v[4:5], v[166:167] op_sel_hi:[1,0]
	v_pk_mul_f32 v[6:7], v[6:7], v[166:167] op_sel_hi:[1,0]
	v_pk_mul_f32 v[8:9], v[8:9], v[166:167] op_sel_hi:[1,0]
	v_pk_mul_f32 v[10:11], v[10:11], v[166:167] op_sel_hi:[1,0]
	v_pk_mul_f32 v[12:13], v[12:13], v[166:167] op_sel_hi:[1,0]
	v_pk_mul_f32 v[14:15], v[14:15], v[166:167] op_sel_hi:[1,0]
	v_pk_mul_f32 v[16:17], v[16:17], v[166:167] op_sel_hi:[1,0]
	v_pk_mul_f32 v[18:19], v[18:19], v[166:167] op_sel_hi:[1,0]
	v_pk_mul_f32 v[20:21], v[20:21], v[166:167] op_sel_hi:[1,0]
	v_pk_mul_f32 v[22:23], v[22:23], v[166:167] op_sel_hi:[1,0]
	v_pk_mul_f32 v[24:25], v[24:25], v[166:167] op_sel_hi:[1,0]
	v_pk_mul_f32 v[26:27], v[26:27], v[166:167] op_sel_hi:[1,0]
	v_pk_mul_f32 v[28:29], v[28:29], v[166:167] op_sel_hi:[1,0]
	v_pk_mul_f32 v[30:31], v[30:31], v[166:167] op_sel_hi:[1,0]
	v_cvt_pk_bf16_f32 v96, v0, v1
	v_cvt_pk_bf16_f32 v97, v2, v3
	v_cvt_pk_bf16_f32 v98, v4, v5
	v_cvt_pk_bf16_f32 v99, v6, v7
	v_cvt_pk_bf16_f32 v100, v16, v17
	v_cvt_pk_bf16_f32 v101, v18, v19
	v_cvt_pk_bf16_f32 v102, v20, v21
	v_cvt_pk_bf16_f32 v103, v22, v23
	v_cvt_pk_bf16_f32 v104, v8, v9
	v_cvt_pk_bf16_f32 v105, v10, v11
	v_cvt_pk_bf16_f32 v106, v12, v13
	v_cvt_pk_bf16_f32 v107, v14, v15
	v_cvt_pk_bf16_f32 v108, v24, v25
	v_cvt_pk_bf16_f32 v109, v26, v27
	v_cvt_pk_bf16_f32 v110, v28, v29
	v_cvt_pk_bf16_f32 v111, v30, v31
	s_nop 1
	v_permlane32_swap_b32_e32 v96, v98
	v_permlane32_swap_b32_e32 v97, v99
	v_permlane32_swap_b32_e32 v100, v102
	v_permlane32_swap_b32_e32 v101, v103
	v_permlane32_swap_b32_e32 v104, v106
	v_permlane32_swap_b32_e32 v105, v107
	v_permlane32_swap_b32_e32 v108, v110
	v_permlane32_swap_b32_e32 v109, v111
	global_store_dwordx4 v172, v[96:99], s[16:17]
	global_store_dwordx4 v172, v[100:103], s[16:17] offset:64
	global_store_dwordx4 v172, v[104:107], s[16:17] offset:32
	global_store_dwordx4 v172, v[108:111], s[16:17] offset:96
	s_mov_b32 s6, s59
	s_mov_b64 s[16:17], s[62:63]
	s_cmp_ge_i32 s6, s8
	s_cbranch_scc0 .Lamla_item

; template <bool MLA>
; DI void attn_phase(const int TID, const int BID, LAS unsigned char* lds, const Params& p, bool need_ctx) {
;     ...
;     const int tid = TID, wid = tid >> 6, lane = tid & 63, r = lane & 31, hh = lane >> 5;
;     const int n_items = 1024 + (need_ctx ? 128 : 0);
;     bf16_t* O = P_WSB(OFF_H);
;     for (int item = BID; item < n_items; item += gridDim.x) {
;         int b, head, row0, nk;
;         if (item < 1024) {
;             const int rnd = item >> 8, w = item & 255, xcd = w & 7, slot = w >> 3, qb = slot & 7;
;             if (MLA) { const int grp = (rnd * 8 + xcd) * 4 + (slot >> 3); b = grp >> 4; head = grp & 15; }
;             else { const int grp = rnd * 8 + xcd; b = grp >> 2; head = (grp & 3) * 4 + (slot >> 3); }
;             row0 = b * 2048 + qb * 256; nk = NKEY;
;         }
;         else { const int it = item - 1024; b = it >> 4; head = it & 15; row0 = TL + b * 256; nk = 256; }
;         const int kvh = MLA ? head : (head >> 2);
;         const bf16_t* Kb = P_WSB(OFF_K) + (size_t)(b * NKV + kvh) * NKEY * 64;
;         const bf16_t* Vb = P_WSB(OFF_VT) + (size_t)(b * NKV + kvh) * NKEY * 64;
;         const bf16_t* Pb = P_WSB(OFF_KPE) + (size_t)b * NKEY * 32;
.LBB0_318:
	s_andn2_b64 vcc, exec, s[4:5]
	s_cbranch_vccnz .LBB0_339
	s_and_b64 vcc, exec, s[2:3]
	s_cbranch_vccnz .LBB0_339
	v_and_b32_e32 v208, 31, v174
	v_bfe_u32 v209, v174, 5, 1
	v_lshrrev_b32_e32 v210, 6, v174
	v_lshrrev_b32_e32 v211, 3, v174
	v_and_b32_e32 v212, 7, v174
	v_mov_b32_e32 v213, s23
	s_movk_i32 s15, 0x90
	v_mad_u32_u24 v243, v208, s15, v213
	v_lshl_add_u32 v243, v209, 4, v243
	v_mad_u32_u24 v218, v211, s15, v213
	v_lshl_add_u32 v218, v212, 4, v218
	s_movk_i32 s15, 0xc0
	v_bfe_u32 v214, v174, 2, 2
	v_lshl_add_u32 v214, v209, 2, v214
	v_mad_u32_u24 v220, v214, s15, v213
	v_bfe_u32 v215, v174, 4, 1
	v_and_b32_e32 v216, 3, v174
	v_lshlrev_b32_e32 v215, 5, v215
	v_lshl_add_u32 v215, v216, 3, v215
	v_add_u32_e32 v220, v220, v215
	v_add_u32_e32 v220, 0x4800, v220
	v_mad_u32_u24 v221, v211, s15, v213
	v_lshl_add_u32 v221, v212, 4, v221
	v_add_u32_e32 v221, 0x4800, v221
	v_lshlrev_b32_e32 v225, 7, v211
	v_lshl_add_u32 v225, v212, 4, v225
	v_lshl_add_u32 v217, v210, 5, v208
	s_movk_i32 s15, 0x800
	v_mul_u32_u24_e32 v171, s15, v217
	v_lshl_add_u32 v171, v209, 4, v171
	v_lshlrev_b32_e32 v172, 11, v217
	v_lshl_add_u32 v172, v209, 4, v172
	v_mov_b32_e32 v167, 0
	v_mov_b32_e32 v246, 0x3f803f80
	v_mov_b32_e32 v247, 0x3f803f80
	v_mov_b32_e32 v248, 0x3f803f80
	v_mov_b32_e32 v249, 0x3f803f80
	v_readfirstlane_b32 s58, v210
	s_mov_b32 s6, s83
	s_lshr_b32 s58, s58, 2
	s_cmpk_gt_i32 s6, 0x3ff
	s_cbranch_scc0 .Lagqa_mainitem_first
	s_add_i32 s21, s6, 0xfffffc00
	s_lshr_b32 s15, s21, 4
	s_and_b32 s18, s21, 15
	s_lshl_b32 s20, s15, 8
	s_add_i32 s20, s20, 0x4000
	s_mov_b32 s7, 0
	s_branch .Lagqa_decoded_first

; #define AT_GLOADK(k0) do { kreg = *(const u32x4*)(Kb + (size_t)((k0) + (tid >> 3)) * 64 + (tid & 7) * 8); \
;             if (MLA) preg = *(const u32x2*)(Pb + (size_t)((k0) + (tid >> 3)) * 32 + (tid & 7) * 4); } while (0)
; #define AT_GLOADV(k0) do { vreg = *(const u32x4*)(Vb + (size_t)((k0) + (tid >> 3)) * 64 + (tid & 7) * 8); } while (0)
; #define AT_WRITEK(buf) do { *(LAS u32x4*)(lds + (buf) * KBUF + (tid >> 3) * KSTR + (tid & 7) * 16) = kreg; \
;             if (MLA) *(LAS u32x2*)(lds + (buf) * KBUF + (tid >> 3) * KSTR + 128 + (tid & 7) * 8) = preg; } while (0)
; #define AT_WRITEV(buf) do { *(LAS u32x4*)(lds + 2 * KBUF + (buf) * VBUF + (tid >> 3) * VSTR + (tid & 7) * 16) = vreg; } while (0)
; template <bool MLA>
; DI void attn_phase(const int TID, const int BID, LAS unsigned char* lds, const Params& p, bool need_ctx) {
;     ...
;         f32x16 o0, o1, sa0, sa1, sb0, sb1;
; #pragma unroll
;         for (int j = 0; j < 16; ++j) { o0[j] = 0.f; o1[j] = 0.f; }
;         float mrun = -1e30f, lsum = 0.f;
;         if (wid >= 4) __builtin_amdgcn_s_setprio(1);
;         const int ntile = nk >> 6;
;         AT_GLOADK(0); AT_GLOADV(0); AT_WRITEK(0); AT_WRITEV(0);
;         AT_GLOADK(64); AT_WRITEK(1);
;         __syncthreads();
;         AT_QK(sa0, sa1, 0);
;         __syncthreads();
.Lagqa_item:
	s_mov_b32 s52, 0x3000
	s_mov_b32 s53, 0x6000
	s_mov_b32 s54, 0
	v_mov_b64_e32 v[0:1], 0
	v_mov_b64_e32 v[2:3], 0
	v_mov_b64_e32 v[4:5], 0
	v_mov_b64_e32 v[6:7], 0
	v_mov_b64_e32 v[8:9], 0
	v_mov_b64_e32 v[10:11], 0
	v_mov_b64_e32 v[12:13], 0
	v_mov_b64_e32 v[14:15], 0
	v_mov_b64_e32 v[16:17], 0
	v_mov_b64_e32 v[18:19], 0
	v_mov_b64_e32 v[20:21], 0
	v_mov_b64_e32 v[22:23], 0
	v_mov_b64_e32 v[24:25], 0
	v_mov_b64_e32 v[26:27], 0
	v_mov_b64_e32 v[28:29], 0
	v_mov_b64_e32 v[30:31], 0
	v_mov_b32_e32 v162, 0xf149f2ca
	v_mov_b32_e32 v164, 0xf149f2ca
	v_mov_b32_e32 v163, 0x7149f2ca
	v_mov_b64_e32 v[226:227], 0
	v_mov_b64_e32 v[228:229], 0
	v_mov_b64_e32 v[230:231], 0
	v_mov_b64_e32 v[232:233], 0
	v_mov_b64_e32 v[234:235], 0
	v_mov_b64_e32 v[236:237], 0
	v_mov_b64_e32 v[238:239], 0
	v_mov_b64_e32 v[240:241], 0
	s_barrier
	s_waitcnt vmcnt(4)
	ds_write_b128 v218, v[136:139]
	s_waitcnt vmcnt(3)
	ds_write_b128 v218, v[140:143] offset:9216
	s_waitcnt vmcnt(2)
	ds_write_b128 v221, v[144:147]
	s_waitcnt lgkmcnt(0)
	s_barrier
	s_cmp_eq_u32 s58, 0
	s_cbranch_scc1 .Lagqa_prio
	s_setprio 1

; template <bool MLA>
; DI void attn_phase(const int TID, const int BID, LAS unsigned char* lds, const Params& p, bool need_ctx) {
;     ...
;             const int rnd = item >> 8, w = item & 255, xcd = w & 7, slot = w >> 3, qb = slot & 7;
;             if (MLA) { const int grp = (rnd * 8 + xcd) * 4 + (slot >> 3); b = grp >> 4; head = grp & 15; }
;             else { const int grp = rnd * 8 + xcd; b = grp >> 2; head = (grp & 3) * 4 + (slot >> 3); }
;             row0 = b * 2048 + qb * 256; nk = NKEY;
;         }
;         else { const int it = item - 1024; b = it >> 4; head = it & 15; row0 = TL + b * 256; nk = 256; }
;         const int kvh = MLA ? head : (head >> 2);
;         const bf16_t* Kb = P_WSB(OFF_K) + (size_t)(b * NKV + kvh) * NKEY * 64;
;         const bf16_t* Vb = P_WSB(OFF_VT) + (size_t)(b * NKV + kvh) * NKEY * 64;
;         const bf16_t* Pb = P_WSB(OFF_KPE) + (size_t)b * NKEY * 32;
;         bf16x8 qf[NKS];
;         {
;             const bf16_t* qp = P_WSB(OFF_Q) + (size_t)(row0 + wid * 32 + r) * QS + head * DK + hh * 8;
; #pragma unroll
;             for (int ks = 0; ks < NKS; ++ks) qf[ks] = *(const bf16x8*)(qp + ks * 16);
;         }
;         u32x4 kreg, vreg; u32x2 preg = {0u, 0u};
.Lagqa_mainitem_next:
	s_lshr_b32 s21, s59, 8
	s_and_b32 s55, s59, 7
	s_lshl_b32 s21, s21, 3
	s_add_i32 s21, s21, s55
	s_bfe_u32 s55, s59, 0x30003
	s_bfe_u32 s56, s59, 0x20006
	s_lshr_b32 s15, s21, 2
	s_and_b32 s57, s21, 3
	s_lshl_b32 s18, s57, 2
	s_add_i32 s18, s18, s56
	s_lshl_b32 s20, s15, 11
	s_lshl_b32 s55, s55, 8
	s_add_i32 s20, s20, s55
	s_mov_b32 s7, 16
.Lagqa_decoded_next:
	s_lshr_b32 s19, s18, 2
	s_lshl_b32 s21, s15, 2
	s_add_i32 s21, s21, s19
	s_mul_i32 s21, s21, 0x48000
	s_add_u32 s2, s26, s21
	s_addc_u32 s3, s27, 0
	v_readlane_b32 s60, v254, 36
	v_readlane_b32 s61, v254, 37
	s_add_u32 s4, s60, s21
	s_addc_u32 s5, s61, 0
	v_readlane_b32 s60, v254, 27
	v_readlane_b32 s61, v254, 28
	s_mul_i32 s21, s20, 0x800
	s_mul_i32 s55, s18, 0x80
	s_add_i32 s21, s21, s55
	s_add_u32 s12, s60, s21
	s_addc_u32 s13, s61, 0
	v_readlane_b32 s60, v254, 34
	v_readlane_b32 s61, v254, 35
	s_lshl_b32 s21, s20, 11
	s_lshl_b32 s55, s18, 7
	s_add_i32 s21, s21, s55
	s_add_u32 s62, s60, s21
	s_addc_u32 s63, s61, 0
	global_load_dwordx4 v[112:115], v171, s[12:13]
	global_load_dwordx4 v[116:119], v171, s[12:13] offset:32
	global_load_dwordx4 v[120:123], v171, s[12:13] offset:64
	global_load_dwordx4 v[124:127], v171, s[12:13] offset:96
	global_load_dwordx4 v[136:139], v225, s[2:3]
	s_add_u32 s2, s2, 0x2000
	s_addc_u32 s3, s3, 0
	global_load_dwordx4 v[140:143], v225, s[2:3]
	s_add_u32 s2, s2, 0x2000
	s_addc_u32 s3, s3, 0
	global_load_dwordx4 v[144:147], v225, s[4:5]
	s_add_u32 s4, s4, 0x2000
	s_addc_u32 s5, s5, 0
	global_load_dwordx4 v[152:155], v225, s[2:3]
	s_add_u32 s2, s2, 0x2000
	s_addc_u32 s3, s3, 0
	global_load_dwordx4 v[156:159], v225, s[4:5]
	s_add_u32 s4, s4, 0x2000
	s_addc_u32 s5, s5, 0
.Lagqa_nonext:
	ds_read_b64_tr_b16 v[192:193], v223 offset:3072
	ds_read_b64_tr_b16 v[194:195], v223 offset:4608
	ds_read_b64_tr_b16 v[196:197], v223 offset:3136
	ds_read_b64_tr_b16 v[198:199], v223 offset:4672
	v_mfma_f32_32x32x16_bf16 v[0:15], v[176:179], v[96:99], v[0:15]
	v_max3_f32 v168, v64, v65, v66
	v_max3_f32 v170, v80, v81, v82
	v_max3_f32 v168, v168, v67, v68
	v_max3_f32 v170, v170, v83, v84
	v_max3_f32 v168, v168, v69, v70
	v_max3_f32 v170, v170, v85, v86
	v_max3_f32 v168, v168, v71, v72
	v_max3_f32 v170, v170, v87, v88
	v_max3_f32 v168, v168, v73, v74
	v_max3_f32 v170, v170, v89, v90
	v_max3_f32 v168, v168, v75, v76
	v_max3_f32 v170, v170, v91, v92
	s_mov_b32 s55, s52
	s_mov_b32 s52, s53
	s_mov_b32 s53, s54
	s_mov_b32 s54, s55
	s_mov_b32 s9, 0
	ds_read_b64_tr_b16 v[200:201], v223 offset:9216
	ds_read_b64_tr_b16 v[202:203], v223 offset:10752
	ds_read_b64_tr_b16 v[204:205], v223 offset:9280
	ds_read_b64_tr_b16 v[206:207], v223 offset:10816
	v_mfma_f32_32x32x16_bf16 v[16:31], v[180:183], v[96:99], v[16:31]
	v_max3_f32 v168, v168, v77, v78
	v_max3_f32 v170, v170, v93, v94
	v_max_f32_e32 v168, v168, v79
	v_max_f32_e32 v170, v170, v95
	v_max_f32_e32 v168, v168, v170
	v_mov_b32_e32 v170, v168
	s_nop 1
	v_permlane32_swap_b32_e32 v168, v170
	v_max_f32_e32 v168, v168, v170
	v_mul_f32_e32 v168, 0x3e38aa3b, v168
	v_cmp_gt_f32_e32 vcc, v168, v164
	s_cbranch_vccz .Lagqa_nors_10
	v_max_f32_e32 v170, v162, v168
	v_sub_f32_e32 v166, v162, v170
	v_exp_f32_e32 v166, v166
	v_mov_b32_e32 v162, v170
	v_add_f32_e32 v164, 0x41000000, v170
	v_xor_b32_e32 v163, 0x80000000, v170
	s_mov_b32 s9, 1
